# norm_rows_b (norm2/norm1-layer1 phases): the two adaLN-modulation load groups per 512-col slab merged into one (4 instead of 8 serialized L2 round trips per call)
# baseline (speedup 1.0000x reference)
.LBB0_762:
	s_nop 0
	v_mov_b32_e32 v0, v179
	v_ashrrev_i32_e32 v65, 31, v64
	v_lshlrev_b32_e32 v0, 3, v0
	v_and_b32_e32 v2, 0x1f8, v0
	v_lshlrev_b64 v[82:83], 12, v[64:65]
	v_lshl_add_u64 v[0:1], s[4:5], 0, v[82:83]
	v_lshlrev_b32_e32 v176, 1, v2
	v_lshl_add_u64 v[0:1], v[0:1], 0, v[176:177]
	global_load_dwordx4 v[52:55], v[0:1], off
	global_load_dwordx4 v[44:47], v[0:1], off offset:1024
	global_load_dwordx4 v[32:35], v[0:1], off offset:2048
	global_load_dwordx4 v[60:63], v[0:1], off offset:3072
	v_add_u32_e32 v0, 8, v64
	v_ashrrev_i32_e32 v1, 31, v0
	v_lshlrev_b64 v[80:81], 12, v[0:1]
	v_lshl_add_u64 v[0:1], s[4:5], 0, v[80:81]
	v_lshl_add_u64 v[0:1], v[0:1], 0, v[176:177]
	global_load_dwordx4 v[56:59], v[0:1], off
	global_load_dwordx4 v[48:51], v[0:1], off offset:1024
	global_load_dwordx4 v[40:43], v[0:1], off offset:2048
	global_load_dwordx4 v[36:39], v[0:1], off offset:3072
	v_add_u32_e32 v0, 16, v64
	v_ashrrev_i32_e32 v1, 31, v0
	v_lshlrev_b64 v[76:77], 12, v[0:1]
	v_lshl_add_u64 v[0:1], s[4:5], 0, v[76:77]
	v_lshl_add_u64 v[4:5], v[0:1], 0, v[176:177]
	v_lshlrev_b32_e32 v66, 2, v2
	global_load_dwordx4 v[20:23], v[4:5], off
	global_load_dwordx4 v[12:15], v[4:5], off offset:1024
	global_load_dwordx4 v[0:3], v[4:5], off offset:2048
	global_load_dwordx4 v[28:31], v[4:5], off offset:3072
	v_add_u32_e32 v4, 24, v64
	v_ashrrev_i32_e32 v5, 31, v4
	v_lshlrev_b64 v[78:79], 12, v[4:5]
	v_lshl_add_u64 v[4:5], s[4:5], 0, v[78:79]
	v_lshl_add_u64 v[4:5], v[4:5], 0, v[176:177]
	global_load_dwordx4 v[24:27], v[4:5], off
	global_load_dwordx4 v[16:19], v[4:5], off offset:1024
	global_load_dwordx4 v[8:11], v[4:5], off offset:2048
	s_nop 0
	global_load_dwordx4 v[4:7], v[4:5], off offset:3072
	v_and_b32_e32 v65, 64, v203
	v_add_u32_e32 v68, 64, v65
	v_xor_b32_e32 v65, 32, v203
	v_cmp_lt_i32_e32 vcc, v65, v68
	v_xor_b32_e32 v67, 16, v203
	v_xor_b32_e32 v69, 8, v203
	v_cndmask_b32_e32 v65, v203, v65, vcc
	v_cmp_lt_i32_e32 vcc, v67, v68
	v_lshlrev_b32_e32 v65, 2, v65
	v_mov_b64_e32 v[116:117], s[16:17]
	v_cndmask_b32_e32 v67, v203, v67, vcc
	v_cmp_lt_i32_e32 vcc, v69, v68
	v_lshlrev_b32_e32 v67, 2, v67
	s_mov_b32 s9, s45
	v_cndmask_b32_e32 v69, v203, v69, vcc
	v_lshlrev_b32_e32 v118, 2, v69
	v_xor_b32_e32 v69, 4, v203
	v_cmp_lt_i32_e32 vcc, v69, v68
	s_add_i32 s10, s10, s22
	s_cmpk_gt_i32 s10, 0x2ff
	v_cndmask_b32_e32 v69, v203, v69, vcc
	v_lshlrev_b32_e32 v119, 2, v69
	v_xor_b32_e32 v69, 2, v203
	v_cmp_lt_i32_e32 vcc, v69, v68
	s_waitcnt vmcnt(0)
	v_and_b32_e32 v123, 0xffff0000, v52
	v_cndmask_b32_e32 v69, v203, v69, vcc
	v_lshlrev_b32_e32 v136, 2, v69
	v_xor_b32_e32 v69, 1, v203
	v_cmp_lt_i32_e32 vcc, v69, v68
	v_and_b32_e32 v131, 0xffff0000, v53
	v_and_b32_e32 v122, 0xffff0000, v56
	v_cndmask_b32_e32 v68, v203, v69, vcc
	v_lshlrev_b32_e32 v137, 2, v68
	v_lshlrev_b32_e32 v69, 16, v61
	v_lshlrev_b32_e32 v68, 16, v60
	v_and_b32_e32 v61, 0xffff0000, v61
	v_and_b32_e32 v60, 0xffff0000, v60
	v_pk_mul_f32 v[70:71], v[60:61], v[60:61]
	v_and_b32_e32 v130, 0xffff0000, v57
	v_pk_fma_f32 v[92:93], v[68:69], v[68:69], v[70:71]
	v_lshlrev_b32_e32 v71, 16, v63
	v_lshlrev_b32_e32 v70, 16, v62
	v_and_b32_e32 v63, 0xffff0000, v63
	v_and_b32_e32 v62, 0xffff0000, v62
	v_pk_mul_f32 v[72:73], v[62:63], v[62:63]
	v_lshlrev_b32_e32 v121, 16, v52
	v_pk_fma_f32 v[94:95], v[70:71], v[70:71], v[72:73]
	v_lshlrev_b32_e32 v120, 16, v56
	v_pk_mul_f32 v[72:73], v[122:123], v[122:123]
	v_lshlrev_b32_e32 v129, 16, v53
	v_lshlrev_b32_e32 v128, 16, v57
	v_pk_mul_f32 v[52:53], v[130:131], v[130:131]
	v_and_b32_e32 v135, 0xffff0000, v54
	v_and_b32_e32 v134, 0xffff0000, v58
	v_lshlrev_b32_e32 v85, 16, v45
	v_and_b32_e32 v87, 0xffff0000, v45
	v_pk_fma_f32 v[72:73], v[120:121], v[120:121], v[72:73]
	v_pk_fma_f32 v[52:53], v[128:129], v[128:129], v[52:53]
	v_lshlrev_b32_e32 v133, 16, v54
	v_lshlrev_b32_e32 v132, 16, v58
	v_pk_mul_f32 v[56:57], v[134:135], v[134:135]
	v_and_b32_e32 v143, 0xffff0000, v55
	v_and_b32_e32 v142, 0xffff0000, v59
	v_lshlrev_b32_e32 v89, 16, v44
	v_and_b32_e32 v91, 0xffff0000, v44
	v_lshlrev_b32_e32 v45, 16, v37
	v_lshlrev_b32_e32 v44, 16, v36
	v_and_b32_e32 v37, 0xffff0000, v37
	v_and_b32_e32 v36, 0xffff0000, v36
	v_pk_add_f32 v[52:53], v[72:73], v[52:53]
	v_pk_fma_f32 v[56:57], v[132:133], v[132:133], v[56:57]
	v_lshlrev_b32_e32 v141, 16, v55
	v_lshlrev_b32_e32 v140, 16, v59
	v_pk_mul_f32 v[54:55], v[142:143], v[142:143]
	v_lshlrev_b32_e32 v88, 16, v48
	v_and_b32_e32 v90, 0xffff0000, v48
	v_lshlrev_b32_e32 v84, 16, v49
	v_and_b32_e32 v86, 0xffff0000, v49
	v_pk_mul_f32 v[48:49], v[36:37], v[36:37]
	v_and_b32_e32 v101, 0xffff0000, v46
	v_pk_fma_f32 v[98:99], v[44:45], v[44:45], v[48:49]
	v_pk_add_f32 v[48:49], v[56:57], v[52:53]
	v_pk_fma_f32 v[52:53], v[140:141], v[140:141], v[54:55]
	v_and_b32_e32 v100, 0xffff0000, v50
	v_pk_add_f32 v[48:49], v[52:53], v[48:49]
	v_pk_mul_f32 v[52:53], v[90:91], v[90:91]
	v_lshlrev_b32_e32 v97, 16, v46
	v_pk_fma_f32 v[52:53], v[88:89], v[88:89], v[52:53]
	v_lshlrev_b32_e32 v96, 16, v50
	v_pk_add_f32 v[48:49], v[52:53], v[48:49]
	v_pk_mul_f32 v[52:53], v[86:87], v[86:87]
	v_and_b32_e32 v109, 0xffff0000, v47
	v_pk_fma_f32 v[52:53], v[84:85], v[84:85], v[52:53]
	v_and_b32_e32 v108, 0xffff0000, v51
	v_pk_add_f32 v[48:49], v[52:53], v[48:49]
	v_pk_mul_f32 v[52:53], v[100:101], v[100:101]
	v_lshlrev_b32_e32 v107, 16, v47
	v_pk_fma_f32 v[52:53], v[96:97], v[96:97], v[52:53]
	v_lshlrev_b32_e32 v106, 16, v51
	v_pk_mul_f32 v[46:47], v[108:109], v[108:109]
	v_pk_add_f32 v[48:49], v[52:53], v[48:49]
	v_pk_fma_f32 v[46:47], v[106:107], v[106:107], v[46:47]
	v_and_b32_e32 v51, 0xffff0000, v32
	v_and_b32_e32 v50, 0xffff0000, v40
	v_pk_add_f32 v[46:47], v[46:47], v[48:49]
	v_lshlrev_b32_e32 v49, 16, v32
	v_lshlrev_b32_e32 v48, 16, v40
	v_pk_mul_f32 v[52:53], v[50:51], v[50:51]
	v_and_b32_e32 v55, 0xffff0000, v33
	v_pk_fma_f32 v[52:53], v[48:49], v[48:49], v[52:53]
	v_and_b32_e32 v54, 0xffff0000, v41
	v_pk_add_f32 v[46:47], v[52:53], v[46:47]
	v_lshlrev_b32_e32 v53, 16, v33
	v_lshlrev_b32_e32 v52, 16, v41
	v_pk_mul_f32 v[32:33], v[54:55], v[54:55]
	v_and_b32_e32 v59, 0xffff0000, v34
	v_and_b32_e32 v58, 0xffff0000, v42
	v_pk_fma_f32 v[32:33], v[52:53], v[52:53], v[32:33]
	v_lshlrev_b32_e32 v57, 16, v34
	v_lshlrev_b32_e32 v56, 16, v42
	v_pk_mul_f32 v[40:41], v[58:59], v[58:59]
	v_and_b32_e32 v75, 0xffff0000, v35
	v_and_b32_e32 v74, 0xffff0000, v43
	v_pk_add_f32 v[32:33], v[32:33], v[46:47]
	v_pk_fma_f32 v[40:41], v[56:57], v[56:57], v[40:41]
	v_lshlrev_b32_e32 v73, 16, v35
	v_lshlrev_b32_e32 v72, 16, v43
	v_pk_mul_f32 v[34:35], v[74:75], v[74:75]
	v_pk_add_f32 v[32:33], v[40:41], v[32:33]
	v_pk_fma_f32 v[34:35], v[72:73], v[72:73], v[34:35]
	v_mov_b32_e32 v43, v94
	v_pk_add_f32 v[32:33], v[34:35], v[32:33]
	v_mov_b32_e32 v34, v98
	v_mov_b32_e32 v35, v92
	v_pk_add_f32 v[40:41], v[34:35], v[32:33]
	v_and_b32_e32 v35, 0xffff0000, v39
	v_and_b32_e32 v34, 0xffff0000, v38
	v_lshlrev_b32_e32 v33, 16, v39
	v_lshlrev_b32_e32 v32, 16, v38
	v_pk_mul_f32 v[38:39], v[34:35], v[34:35]
	v_mov_b32_e32 v92, v99
	v_pk_fma_f32 v[38:39], v[32:33], v[32:33], v[38:39]
	v_pk_add_f32 v[40:41], v[92:93], v[40:41]
	v_mov_b32_e32 v42, v38
	v_pk_add_f32 v[40:41], v[42:43], v[40:41]
	v_lshlrev_b32_e32 v43, 16, v29
	v_lshlrev_b32_e32 v42, 16, v28
	v_and_b32_e32 v29, 0xffff0000, v29
	v_and_b32_e32 v28, 0xffff0000, v28
	v_pk_mul_f32 v[46:47], v[28:29], v[28:29]
	v_and_b32_e32 v159, 0xffff0000, v20
	v_pk_fma_f32 v[138:139], v[42:43], v[42:43], v[46:47]
	v_lshlrev_b32_e32 v47, 16, v31
	v_lshlrev_b32_e32 v46, 16, v30
	v_and_b32_e32 v31, 0xffff0000, v31
	v_and_b32_e32 v30, 0xffff0000, v30
	v_pk_mul_f32 v[92:93], v[30:31], v[30:31]
	v_and_b32_e32 v158, 0xffff0000, v24
	v_and_b32_e32 v163, 0xffff0000, v21
	v_and_b32_e32 v162, 0xffff0000, v25
	v_pk_fma_f32 v[172:173], v[46:47], v[46:47], v[92:93]
	v_lshlrev_b32_e32 v157, 16, v20
	v_lshlrev_b32_e32 v156, 16, v24
	v_pk_mul_f32 v[92:93], v[158:159], v[158:159]
	v_lshlrev_b32_e32 v161, 16, v21
	v_lshlrev_b32_e32 v160, 16, v25
	v_pk_mul_f32 v[20:21], v[162:163], v[162:163]
	v_pk_fma_f32 v[92:93], v[156:157], v[156:157], v[92:93]
	v_pk_fma_f32 v[20:21], v[160:161], v[160:161], v[20:21]
	v_and_b32_e32 v167, 0xffff0000, v22
	v_and_b32_e32 v166, 0xffff0000, v26
	v_pk_add_f32 v[24:25], v[92:93], v[20:21]
	v_lshlrev_b32_e32 v165, 16, v22
	v_lshlrev_b32_e32 v164, 16, v26
	v_pk_mul_f32 v[20:21], v[166:167], v[166:167]
	v_and_b32_e32 v171, 0xffff0000, v23
	v_and_b32_e32 v170, 0xffff0000, v27
	v_pk_fma_f32 v[92:93], v[164:165], v[164:165], v[20:21]
	v_lshlrev_b32_e32 v169, 16, v23
	v_lshlrev_b32_e32 v168, 16, v27
	v_pk_mul_f32 v[22:23], v[170:171], v[170:171]
	v_lshlrev_b32_e32 v125, 16, v13
	v_and_b32_e32 v127, 0xffff0000, v13
	v_lshlrev_b32_e32 v145, 16, v12
	v_and_b32_e32 v147, 0xffff0000, v12
	v_and_b32_e32 v146, 0xffff0000, v16
	v_pk_add_f32 v[12:13], v[92:93], v[24:25]
	v_pk_fma_f32 v[22:23], v[168:169], v[168:169], v[22:23]
	v_lshlrev_b32_e32 v144, 16, v16
	v_pk_add_f32 v[12:13], v[22:23], v[12:13]
	v_pk_mul_f32 v[22:23], v[146:147], v[146:147]
	v_and_b32_e32 v126, 0xffff0000, v17
	v_pk_fma_f32 v[22:23], v[144:145], v[144:145], v[22:23]
	v_lshlrev_b32_e32 v124, 16, v17
	v_pk_add_f32 v[12:13], v[22:23], v[12:13]
	v_pk_mul_f32 v[22:23], v[126:127], v[126:127]
	v_and_b32_e32 v151, 0xffff0000, v14
	v_pk_fma_f32 v[22:23], v[124:125], v[124:125], v[22:23]
	v_and_b32_e32 v150, 0xffff0000, v18
	v_pk_add_f32 v[12:13], v[22:23], v[12:13]
	v_lshlrev_b32_e32 v149, 16, v14
	v_lshlrev_b32_e32 v148, 16, v18
	v_pk_mul_f32 v[22:23], v[150:151], v[150:151]
	v_and_b32_e32 v155, 0xffff0000, v15
	v_and_b32_e32 v154, 0xffff0000, v19
	v_mov_b32_e32 v94, v39
	v_pk_fma_f32 v[22:23], v[148:149], v[148:149], v[22:23]
	v_lshlrev_b32_e32 v153, 16, v15
	v_lshlrev_b32_e32 v152, 16, v19
	v_pk_mul_f32 v[14:15], v[154:155], v[154:155]
	v_pk_add_f32 v[38:39], v[94:95], v[40:41]
	v_pk_add_f32 v[12:13], v[22:23], v[12:13]
	v_pk_fma_f32 v[14:15], v[152:153], v[152:153], v[14:15]
	v_and_b32_e32 v95, 0xffff0000, v0
	v_and_b32_e32 v94, 0xffff0000, v8
	v_pk_add_f32 v[12:13], v[14:15], v[12:13]
	v_lshlrev_b32_e32 v93, 16, v0
	v_lshlrev_b32_e32 v92, 16, v8
	v_pk_mul_f32 v[14:15], v[94:95], v[94:95]
	v_and_b32_e32 v103, 0xffff0000, v1
	v_and_b32_e32 v102, 0xffff0000, v9
	v_pk_fma_f32 v[14:15], v[92:93], v[92:93], v[14:15]
	v_lshlrev_b32_e32 v99, 16, v1
	v_lshlrev_b32_e32 v98, 16, v9
	v_pk_mul_f32 v[0:1], v[102:103], v[102:103]
	v_and_b32_e32 v111, 0xffff0000, v2
	v_and_b32_e32 v110, 0xffff0000, v10
	v_and_b32_e32 v21, 0xffff0000, v5
	v_and_b32_e32 v20, 0xffff0000, v4
	v_pk_add_f32 v[12:13], v[14:15], v[12:13]
	v_pk_fma_f32 v[0:1], v[98:99], v[98:99], v[0:1]
	v_lshlrev_b32_e32 v105, 16, v2
	v_lshlrev_b32_e32 v104, 16, v10
	v_pk_mul_f32 v[8:9], v[110:111], v[110:111]
	v_and_b32_e32 v115, 0xffff0000, v3
	v_and_b32_e32 v114, 0xffff0000, v11
	v_lshlrev_b32_e32 v17, 16, v5
	v_lshlrev_b32_e32 v16, 16, v4
	v_pk_mul_f32 v[4:5], v[20:21], v[20:21]
	v_pk_add_f32 v[0:1], v[0:1], v[12:13]
	v_pk_fma_f32 v[8:9], v[104:105], v[104:105], v[8:9]
	v_lshlrev_b32_e32 v113, 16, v3
	v_lshlrev_b32_e32 v112, 16, v11
	v_pk_mul_f32 v[2:3], v[114:115], v[114:115]
	ds_bpermute_b32 v41, v65, v39
	ds_bpermute_b32 v40, v65, v38
	v_pk_fma_f32 v[4:5], v[16:17], v[16:17], v[4:5]
	v_pk_add_f32 v[0:1], v[8:9], v[0:1]
	v_pk_fma_f32 v[2:3], v[112:113], v[112:113], v[2:3]
	v_and_b32_e32 v19, 0xffff0000, v7
	v_pk_add_f32 v[0:1], v[2:3], v[0:1]
	v_mov_b32_e32 v2, v4
	v_mov_b32_e32 v3, v138
	v_and_b32_e32 v18, 0xffff0000, v6
	v_pk_add_f32 v[0:1], v[2:3], v[0:1]
	v_lshlrev_b32_e32 v23, 16, v7
	v_lshlrev_b32_e32 v22, 16, v6
	v_pk_mul_f32 v[2:3], v[18:19], v[18:19]
	v_mov_b32_e32 v138, v5
	v_pk_fma_f32 v[2:3], v[22:23], v[22:23], v[2:3]
	v_pk_add_f32 v[0:1], v[138:139], v[0:1]
	v_mov_b32_e32 v4, v2
	v_mov_b32_e32 v5, v172
	s_waitcnt lgkmcnt(0)
	v_pk_add_f32 v[38:39], v[38:39], v[40:41]
	v_pk_add_f32 v[0:1], v[4:5], v[0:1]
	v_mov_b32_e32 v172, v3
	ds_bpermute_b32 v41, v67, v39
	ds_bpermute_b32 v40, v67, v38
	v_pk_add_f32 v[0:1], v[172:173], v[0:1]
	ds_bpermute_b32 v3, v65, v1
	ds_bpermute_b32 v2, v65, v0
	s_waitcnt lgkmcnt(2)
	v_pk_add_f32 v[38:39], v[38:39], v[40:41]
	ds_bpermute_b32 v41, v118, v39
	ds_bpermute_b32 v40, v118, v38
	s_waitcnt lgkmcnt(2)
	v_pk_add_f32 v[0:1], v[0:1], v[2:3]
	ds_bpermute_b32 v3, v67, v1
	ds_bpermute_b32 v2, v67, v0
	v_mov_b32_e32 v67, v177
	s_waitcnt lgkmcnt(2)
	v_pk_add_f32 v[38:39], v[38:39], v[40:41]
	ds_bpermute_b32 v41, v119, v39
	ds_bpermute_b32 v40, v119, v38
	s_waitcnt lgkmcnt(2)
	v_pk_add_f32 v[0:1], v[0:1], v[2:3]
	ds_bpermute_b32 v3, v118, v1
	ds_bpermute_b32 v2, v118, v0
	s_waitcnt lgkmcnt(2)
	v_pk_add_f32 v[38:39], v[38:39], v[40:41]
	ds_bpermute_b32 v41, v136, v39
	ds_bpermute_b32 v40, v136, v38
	s_waitcnt lgkmcnt(2)
	v_pk_add_f32 v[0:1], v[0:1], v[2:3]
	ds_bpermute_b32 v3, v119, v1
	ds_bpermute_b32 v2, v119, v0
	s_waitcnt lgkmcnt(2)
	v_pk_add_f32 v[38:39], v[38:39], v[40:41]
	ds_bpermute_b32 v41, v137, v39
	ds_bpermute_b32 v40, v137, v38
	s_waitcnt lgkmcnt(2)
	v_pk_add_f32 v[0:1], v[0:1], v[2:3]
	ds_bpermute_b32 v3, v136, v1
	ds_bpermute_b32 v2, v136, v0
	s_waitcnt lgkmcnt(2)
	v_pk_add_f32 v[38:39], v[38:39], v[40:41]
	s_nop 0
	v_pk_fma_f32 v[38:39], v[38:39], s[12:13], v[116:117] op_sel_hi:[1,0,0]
	s_waitcnt lgkmcnt(0)
	v_pk_add_f32 v[0:1], v[0:1], v[2:3]
	v_mul_f32_e32 v40, 0x4b800000, v39
	v_cmp_gt_f32_e64 s[6:7], s14, v39
	ds_bpermute_b32 v3, v137, v1
	ds_bpermute_b32 v2, v137, v0
	v_cndmask_b32_e64 v39, v39, v40, s[6:7]
	v_rsq_f32_e32 v39, v39
	v_cmp_gt_f32_e32 vcc, s14, v38
	s_waitcnt lgkmcnt(0)
	v_pk_add_f32 v[0:1], v[0:1], v[2:3]
	v_mul_f32_e32 v40, 0x45800000, v39
	v_pk_fma_f32 v[0:1], v[0:1], s[12:13], v[116:117] op_sel_hi:[1,0,0]
	v_cndmask_b32_e64 v40, v39, v40, s[6:7]
	v_mul_f32_e32 v39, 0x4b800000, v38
	v_mul_f32_e32 v2, 0x4b800000, v1
	v_cmp_gt_f32_e64 s[6:7], s14, v1
	v_cndmask_b32_e32 v38, v38, v39, vcc
	v_rsq_f32_e32 v38, v38
	v_cndmask_b32_e64 v1, v1, v2, s[6:7]
	v_rsq_f32_e32 v1, v1
	v_mul_f32_e32 v39, 0x45800000, v38
	v_cndmask_b32_e32 v38, v38, v39, vcc
	v_mul_f32_e32 v2, 0x45800000, v1
	v_cmp_gt_f32_e32 vcc, s14, v0
	v_cndmask_b32_e64 v26, v1, v2, s[6:7]
	v_mul_f32_e32 v1, 0x4b800000, v0
	v_cndmask_b32_e32 v0, v0, v1, vcc
	v_rsq_f32_e32 v0, v0
	s_nop 0
	v_mul_f32_e32 v1, 0x45800000, v0
	v_cndmask_b32_e32 v24, v0, v1, vcc
	v_add_u32_e32 v0, 0xffffe000, v64
	v_lshrrev_b32_e32 v0, 11, v0
	v_cmp_lt_i32_e32 vcc, s21, v64
	v_add_u32_e32 v64, s11, v64
	s_nop 0
	v_cndmask_b32_e32 v4, 8, v0, vcc
	v_add_u32_e32 v2, s0, v4
	v_mov_b64_e32 v[0:1], s[18:19]
	v_mad_u64_u32 v[2:3], s[6:7], v2, s29, v[0:1]
	v_add_u32_e32 v4, s1, v4
	v_lshl_add_u64 v[136:137], v[2:3], 0, s[44:45]
	v_mad_u64_u32 v[0:1], s[6:7], v4, s29, v[0:1]
	v_lshl_add_u64 v[138:139], v[0:1], 0, s[44:45]
	v_lshl_add_u64 v[182:183], v[136:137], 0, v[66:67]
	v_lshl_add_u64 v[116:117], v[2:3], 0, s[8:9]
	v_lshl_add_u64 v[118:119], v[0:1], 0, s[8:9]
	global_load_dwordx4 v[0:3], v66, s[2:3] offset:16
	global_load_dwordx4 v[4:7], v66, s[2:3]
	v_lshl_add_u64 v[172:173], v[138:139], 0, v[66:67]
	global_load_dwordx4 v[8:11], v[182:183], off offset:16
	global_load_dwordx4 v[12:15], v[182:183], off
	global_load_dwordx4 v[184:187], v[172:173], off offset:16
	global_load_dwordx4 v[188:191], v[172:173], off
	v_lshl_add_u64 v[192:193], v[116:117], 0, v[66:67]
	v_lshl_add_u64 v[174:175], v[118:119], 0, v[66:67]
	global_load_dwordx4 v[208:211], v[192:193], off offset:16
	global_load_dwordx4 v[212:215], v[192:193], off
	global_load_dwordx4 v[216:219], v[174:175], off offset:16
	global_load_dwordx4 v[220:223], v[174:175], off
	s_waitcnt vmcnt(0)
	v_pk_add_f32 v[14:15], v[14:15], v[190:191]
	v_pk_add_f32 v[12:13], v[12:13], v[188:189]
	v_pk_add_f32 v[14:15], v[14:15], 1.0 op_sel_hi:[1,0]
	v_pk_add_f32 v[12:13], v[12:13], 1.0 op_sel_hi:[1,0]
	v_pk_mul_f32 v[188:189], v[6:7], v[14:15]
	v_pk_mul_f32 v[190:191], v[4:5], v[12:13]
	v_pk_add_f32 v[4:5], v[10:11], v[186:187]
	v_pk_add_f32 v[6:7], v[8:9], v[184:185]
	v_pk_add_f32 v[4:5], v[4:5], 1.0 op_sel_hi:[1,0]
	v_pk_add_f32 v[6:7], v[6:7], 1.0 op_sel_hi:[1,0]
	v_pk_mul_f32 v[184:185], v[2:3], v[4:5]
	v_pk_mul_f32 v[186:187], v[0:1], v[6:7]
	v_pk_add_f32 v[180:181], v[208:209], v[216:217]
	v_pk_add_f32 v[10:11], v[214:215], v[222:223]
	v_pk_add_f32 v[14:15], v[210:211], v[218:219]
	v_mov_b32_e32 v2, v129
	v_mov_b32_e32 v3, v131
	v_mov_b32_e32 v0, v121
	v_mov_b32_e32 v1, v123
	v_pk_mul_f32 v[2:3], v[40:41], v[2:3] op_sel_hi:[0,1]
	v_pk_add_f32 v[12:13], v[212:213], v[220:221]
	v_pk_mul_f32 v[0:1], v[40:41], v[0:1] op_sel_hi:[0,1]
	v_pk_fma_f32 v[4:5], v[2:3], v[188:189], v[10:11]
	v_mov_b32_e32 v2, v133
	v_mov_b32_e32 v3, v135
	v_pk_fma_f32 v[0:1], v[0:1], v[190:191], v[12:13]
	v_pk_mul_f32 v[2:3], v[40:41], v[2:3] op_sel_hi:[0,1]
	v_mov_b32_e32 v6, v141
	v_mov_b32_e32 v7, v143
	v_pk_mul_f32 v[6:7], v[40:41], v[6:7] op_sel_hi:[0,1]
	v_pk_fma_f32 v[8:9], v[2:3], v[186:187], v[180:181]
	v_cvt_pk_bf16_f32 v2, v0, v1
	v_lshl_add_u64 v[0:1], s[34:35], 0, v[82:83]
	v_pk_fma_f32 v[6:7], v[6:7], v[184:185], v[14:15]
	v_cvt_pk_bf16_f32 v3, v4, v5
	v_cvt_pk_bf16_f32 v4, v8, v9
	v_lshl_add_u64 v[0:1], v[0:1], 0, v[176:177]
	v_cvt_pk_bf16_f32 v5, v6, v7
	v_mov_b32_e32 v121, v122
	v_mov_b32_e32 v129, v130
	global_store_dwordx4 v[0:1], v[2:5], off
	v_mov_b32_e32 v133, v134
	v_mov_b32_e32 v141, v142
	v_pk_mul_f32 v[2:3], v[38:39], v[120:121] op_sel_hi:[0,1]
	v_pk_mul_f32 v[4:5], v[38:39], v[128:129] op_sel_hi:[0,1]
	v_pk_fma_f32 v[6:7], v[4:5], v[188:189], v[10:11]
	v_pk_fma_f32 v[2:3], v[2:3], v[190:191], v[12:13]
	v_pk_mul_f32 v[4:5], v[38:39], v[132:133] op_sel_hi:[0,1]
	v_pk_mul_f32 v[8:9], v[38:39], v[140:141] op_sel_hi:[0,1]
	v_pk_fma_f32 v[82:83], v[4:5], v[186:187], v[180:181]
	v_cvt_pk_bf16_f32 v4, v2, v3
	v_lshl_add_u64 v[2:3], s[34:35], 0, v[80:81]
	v_pk_fma_f32 v[8:9], v[8:9], v[184:185], v[14:15]
	v_cvt_pk_bf16_f32 v5, v6, v7
	v_cvt_pk_bf16_f32 v6, v82, v83
	v_lshl_add_u64 v[2:3], v[2:3], 0, v[176:177]
	v_cvt_pk_bf16_f32 v7, v8, v9
	global_store_dwordx4 v[2:3], v[4:7], off
	v_mov_b32_e32 v80, v169
	v_mov_b32_e32 v81, v171
	v_mov_b32_e32 v6, v161
	v_mov_b32_e32 v7, v163
	v_mov_b32_e32 v4, v157
	v_mov_b32_e32 v5, v159
	v_pk_mul_f32 v[6:7], v[26:27], v[6:7] op_sel_hi:[0,1]
	v_pk_mul_f32 v[4:5], v[26:27], v[4:5] op_sel_hi:[0,1]
	v_pk_fma_f32 v[8:9], v[6:7], v[188:189], v[10:11]
	v_mov_b32_e32 v6, v165
	v_mov_b32_e32 v7, v167
	v_pk_fma_f32 v[4:5], v[4:5], v[190:191], v[12:13]
	v_pk_mul_f32 v[6:7], v[26:27], v[6:7] op_sel_hi:[0,1]
	v_pk_mul_f32 v[80:81], v[26:27], v[80:81] op_sel_hi:[0,1]
	v_pk_fma_f32 v[82:83], v[6:7], v[186:187], v[180:181]
	v_cvt_pk_bf16_f32 v6, v4, v5
	v_lshl_add_u64 v[4:5], s[34:35], 0, v[76:77]
	v_pk_fma_f32 v[80:81], v[80:81], v[184:185], v[14:15]
	v_cvt_pk_bf16_f32 v7, v8, v9
	v_cvt_pk_bf16_f32 v8, v82, v83
	v_lshl_add_u64 v[4:5], v[4:5], 0, v[176:177]
	v_cvt_pk_bf16_f32 v9, v80, v81
	v_mov_b32_e32 v157, v158
	v_mov_b32_e32 v161, v162
	global_store_dwordx4 v[4:5], v[6:9], off
	v_mov_b32_e32 v165, v166
	v_mov_b32_e32 v169, v170
	v_pk_mul_f32 v[6:7], v[24:25], v[156:157] op_sel_hi:[0,1]
	v_pk_mul_f32 v[8:9], v[24:25], v[160:161] op_sel_hi:[0,1]
	v_pk_fma_f32 v[10:11], v[188:189], v[8:9], v[10:11]
	v_pk_fma_f32 v[6:7], v[190:191], v[6:7], v[12:13]
	v_pk_mul_f32 v[8:9], v[24:25], v[164:165] op_sel_hi:[0,1]
	v_pk_mul_f32 v[12:13], v[24:25], v[168:169] op_sel_hi:[0,1]
	v_pk_fma_f32 v[12:13], v[184:185], v[12:13], v[14:15]
	v_pk_fma_f32 v[14:15], v[186:187], v[8:9], v[180:181]
	v_cvt_pk_bf16_f32 v8, v6, v7
	v_lshl_add_u64 v[6:7], s[34:35], 0, v[78:79]
	v_lshl_add_u64 v[6:7], v[6:7], 0, v[176:177]
	v_cvt_pk_bf16_f32 v9, v10, v11
	v_cvt_pk_bf16_f32 v10, v14, v15
	v_cvt_pk_bf16_f32 v11, v12, v13
	global_store_dwordx4 v[6:7], v[8:11], off
	global_load_dwordx4 v[76:79], v66, s[2:3] offset:2064
	s_nop 0
	global_load_dwordx4 v[8:11], v66, s[2:3] offset:2048
	global_load_dwordx4 v[80:83], v[182:183], off offset:2064
	global_load_dwordx4 v[12:15], v[182:183], off offset:2048
	global_load_dwordx4 v[120:123], v[172:173], off offset:2064
	global_load_dwordx4 v[128:131], v[172:173], off offset:2048
	v_or_b32_e32 v176, 0x1000, v66
	global_load_dwordx4 v[208:211], v[192:193], off offset:2064
	global_load_dwordx4 v[212:215], v[192:193], off offset:2048
	global_load_dwordx4 v[216:219], v[174:175], off offset:2064
	global_load_dwordx4 v[220:223], v[174:175], off offset:2048
	s_waitcnt vmcnt(0)
	v_pk_add_f32 v[14:15], v[14:15], v[130:131]
	v_pk_add_f32 v[12:13], v[12:13], v[128:129]
	v_pk_add_f32 v[14:15], v[14:15], 1.0 op_sel_hi:[1,0]
	v_pk_add_f32 v[128:129], v[12:13], 1.0 op_sel_hi:[1,0]
	v_pk_mul_f32 v[12:13], v[10:11], v[14:15]
	v_pk_mul_f32 v[14:15], v[8:9], v[128:129]
	v_pk_add_f32 v[8:9], v[82:83], v[122:123]
	v_pk_add_f32 v[10:11], v[80:81], v[120:121]
	v_pk_add_f32 v[8:9], v[8:9], 1.0 op_sel_hi:[1,0]
	v_pk_add_f32 v[10:11], v[10:11], 1.0 op_sel_hi:[1,0]
	v_pk_mul_f32 v[8:9], v[78:79], v[8:9]
	v_pk_mul_f32 v[10:11], v[76:77], v[10:11]
	v_pk_add_f32 v[120:121], v[208:209], v[216:217]
	v_mov_b32_e32 v76, v89
	v_mov_b32_e32 v77, v91
	v_pk_add_f32 v[80:81], v[212:213], v[220:221]
	v_pk_add_f32 v[122:123], v[210:211], v[218:219]
	v_pk_mul_f32 v[76:77], v[40:41], v[76:77] op_sel_hi:[0,1]
	v_mov_b32_e32 v78, v85
	v_mov_b32_e32 v79, v87
	v_pk_add_f32 v[82:83], v[214:215], v[222:223]
	v_pk_mul_f32 v[78:79], v[40:41], v[78:79] op_sel_hi:[0,1]
	v_pk_fma_f32 v[76:77], v[76:77], v[14:15], v[80:81]
	v_mov_b32_e32 v128, v97
	v_mov_b32_e32 v129, v101
	v_mov_b32_e32 v130, v107
	v_mov_b32_e32 v131, v109
	v_pk_fma_f32 v[78:79], v[78:79], v[12:13], v[82:83]
	v_pk_mul_f32 v[128:129], v[40:41], v[128:129] op_sel_hi:[0,1]
	v_pk_mul_f32 v[130:131], v[40:41], v[130:131] op_sel_hi:[0,1]
	v_cvt_pk_bf16_f32 v76, v76, v77
	v_cvt_pk_bf16_f32 v77, v78, v79
	v_mov_b32_e32 v89, v90
	v_pk_fma_f32 v[130:131], v[130:131], v[8:9], v[122:123]
	v_pk_fma_f32 v[128:129], v[128:129], v[10:11], v[120:121]
	v_mov_b32_e32 v85, v86
	v_cvt_pk_bf16_f32 v78, v128, v129
	v_cvt_pk_bf16_f32 v79, v130, v131
	global_store_dwordx4 v[0:1], v[76:79], off offset:1024
	v_mov_b32_e32 v97, v100
	v_mov_b32_e32 v107, v108
	v_pk_mul_f32 v[76:77], v[38:39], v[88:89] op_sel_hi:[0,1]
	v_pk_mul_f32 v[78:79], v[38:39], v[84:85] op_sel_hi:[0,1]
	v_pk_fma_f32 v[76:77], v[76:77], v[14:15], v[80:81]
	v_pk_fma_f32 v[78:79], v[78:79], v[12:13], v[82:83]
	v_pk_mul_f32 v[84:85], v[38:39], v[96:97] op_sel_hi:[0,1]
	v_pk_mul_f32 v[86:87], v[38:39], v[106:107] op_sel_hi:[0,1]
	v_cvt_pk_bf16_f32 v76, v76, v77
	v_cvt_pk_bf16_f32 v77, v78, v79
	v_pk_fma_f32 v[86:87], v[86:87], v[8:9], v[122:123]
	v_pk_fma_f32 v[84:85], v[84:85], v[10:11], v[120:121]
	v_lshl_add_u64 v[88:89], v[138:139], 0, v[176:177]
	v_cvt_pk_bf16_f32 v78, v84, v85
	v_cvt_pk_bf16_f32 v79, v86, v87
	global_store_dwordx4 v[2:3], v[76:79], off offset:1024
	v_mov_b32_e32 v84, v149
	v_mov_b32_e32 v85, v151
	v_mov_b32_e32 v76, v145
	v_mov_b32_e32 v77, v147
	v_pk_mul_f32 v[76:77], v[26:27], v[76:77] op_sel_hi:[0,1]
	v_mov_b32_e32 v78, v125
	v_mov_b32_e32 v79, v127
	v_pk_mul_f32 v[78:79], v[26:27], v[78:79] op_sel_hi:[0,1]
	v_pk_fma_f32 v[76:77], v[76:77], v[14:15], v[80:81]
	v_mov_b32_e32 v86, v153
	v_mov_b32_e32 v87, v155
	v_pk_fma_f32 v[78:79], v[78:79], v[12:13], v[82:83]
	v_pk_mul_f32 v[84:85], v[26:27], v[84:85] op_sel_hi:[0,1]
	v_pk_mul_f32 v[86:87], v[26:27], v[86:87] op_sel_hi:[0,1]
	v_cvt_pk_bf16_f32 v76, v76, v77
	v_cvt_pk_bf16_f32 v77, v78, v79
	v_mov_b32_e32 v145, v146
	v_pk_fma_f32 v[86:87], v[86:87], v[8:9], v[122:123]
	v_pk_fma_f32 v[84:85], v[84:85], v[10:11], v[120:121]
	v_mov_b32_e32 v125, v126
	v_cvt_pk_bf16_f32 v78, v84, v85
	v_cvt_pk_bf16_f32 v79, v86, v87
	global_store_dwordx4 v[4:5], v[76:79], off offset:1024
	v_mov_b32_e32 v149, v150
	v_mov_b32_e32 v153, v154
	v_pk_mul_f32 v[76:77], v[24:25], v[144:145] op_sel_hi:[0,1]
	v_pk_mul_f32 v[78:79], v[24:25], v[124:125] op_sel_hi:[0,1]
	v_pk_fma_f32 v[14:15], v[76:77], v[14:15], v[80:81]
	v_pk_mul_f32 v[76:77], v[24:25], v[148:149] op_sel_hi:[0,1]
	v_pk_fma_f32 v[12:13], v[78:79], v[12:13], v[82:83]
	v_pk_mul_f32 v[78:79], v[24:25], v[152:153] op_sel_hi:[0,1]
	v_pk_fma_f32 v[10:11], v[76:77], v[10:11], v[120:121]
	v_pk_fma_f32 v[78:79], v[78:79], v[8:9], v[122:123]
	v_cvt_pk_bf16_f32 v8, v14, v15
	v_cvt_pk_bf16_f32 v9, v12, v13
	v_cvt_pk_bf16_f32 v10, v10, v11
	v_lshl_add_u64 v[12:13], v[136:137], 0, v[176:177]
	v_cvt_pk_bf16_f32 v11, v78, v79
	global_store_dwordx4 v[6:7], v[8:11], off offset:1024
	global_load_dwordx4 v[76:79], v176, s[2:3] offset:16
	s_nop 0
	global_load_dwordx4 v[8:11], v176, s[2:3]
	global_load_dwordx4 v[80:83], v[12:13], off offset:16
	s_nop 0
	global_load_dwordx4 v[12:15], v[12:13], off
	s_nop 0
	global_load_dwordx4 v[84:87], v[88:89], off offset:16
	s_nop 0
	global_load_dwordx4 v[88:91], v[88:89], off
	v_lshl_add_u64 v[224:225], v[116:117], 0, v[176:177]
	v_lshl_add_u64 v[226:227], v[118:119], 0, v[176:177]
	global_load_dwordx4 v[208:211], v[224:225], off offset:16
	global_load_dwordx4 v[212:215], v[224:225], off
	global_load_dwordx4 v[216:219], v[226:227], off offset:16
	global_load_dwordx4 v[220:223], v[226:227], off
	s_waitcnt vmcnt(0)
	v_pk_add_f32 v[14:15], v[14:15], v[90:91]
	v_pk_add_f32 v[12:13], v[12:13], v[88:89]
	v_pk_add_f32 v[14:15], v[14:15], 1.0 op_sel_hi:[1,0]
	v_pk_add_f32 v[88:89], v[12:13], 1.0 op_sel_hi:[1,0]
	v_pk_mul_f32 v[12:13], v[10:11], v[14:15]
	v_pk_mul_f32 v[14:15], v[8:9], v[88:89]
	v_pk_add_f32 v[8:9], v[82:83], v[86:87]
	v_pk_add_f32 v[10:11], v[80:81], v[84:85]
	v_pk_add_f32 v[8:9], v[8:9], 1.0 op_sel_hi:[1,0]
	v_pk_add_f32 v[10:11], v[10:11], 1.0 op_sel_hi:[1,0]
	v_pk_mul_f32 v[8:9], v[78:79], v[8:9]
	v_pk_mul_f32 v[10:11], v[76:77], v[10:11]
	v_or_b32_e32 v176, 0x1800, v66
	v_lshl_add_u64 v[66:67], v[138:139], 0, v[176:177]
	v_pk_add_f32 v[86:87], v[210:211], v[218:219]
	v_pk_add_f32 v[84:85], v[208:209], v[216:217]
	v_mov_b32_e32 v76, v49
	v_mov_b32_e32 v77, v51
	v_mov_b32_e32 v78, v53
	v_mov_b32_e32 v79, v55
	v_mov_b32_e32 v49, v50
	v_pk_add_f32 v[82:83], v[214:215], v[222:223]
	v_pk_add_f32 v[80:81], v[212:213], v[220:221]
	v_pk_mul_f32 v[76:77], v[40:41], v[76:77] op_sel_hi:[0,1]
	v_pk_mul_f32 v[78:79], v[40:41], v[78:79] op_sel_hi:[0,1]
	v_mov_b32_e32 v88, v57
	v_mov_b32_e32 v89, v59
	v_mov_b32_e32 v90, v73
	v_mov_b32_e32 v91, v75
	v_pk_mul_f32 v[48:49], v[38:39], v[48:49] op_sel_hi:[0,1]
	v_mov_b32_e32 v53, v54
	v_pk_fma_f32 v[78:79], v[78:79], v[12:13], v[82:83]
	v_pk_fma_f32 v[76:77], v[76:77], v[14:15], v[80:81]
	v_pk_mul_f32 v[88:89], v[40:41], v[88:89] op_sel_hi:[0,1]
	v_pk_mul_f32 v[90:91], v[40:41], v[90:91] op_sel_hi:[0,1]
	v_pk_mul_f32 v[50:51], v[38:39], v[52:53] op_sel_hi:[0,1]
	v_pk_fma_f32 v[48:49], v[48:49], v[14:15], v[80:81]
	v_mov_b32_e32 v57, v58
	v_mov_b32_e32 v73, v74
	v_pk_fma_f32 v[90:91], v[90:91], v[8:9], v[86:87]
	v_pk_fma_f32 v[88:89], v[88:89], v[10:11], v[84:85]
	v_cvt_pk_bf16_f32 v76, v76, v77
	v_cvt_pk_bf16_f32 v77, v78, v79
	v_pk_fma_f32 v[50:51], v[50:51], v[12:13], v[82:83]
	v_cvt_pk_bf16_f32 v78, v88, v89
	v_cvt_pk_bf16_f32 v79, v90, v91
	global_store_dwordx4 v[0:1], v[76:79], off offset:2048
	v_pk_mul_f32 v[52:53], v[38:39], v[56:57] op_sel_hi:[0,1]
	v_pk_mul_f32 v[54:55], v[38:39], v[72:73] op_sel_hi:[0,1]
	v_cvt_pk_bf16_f32 v48, v48, v49
	v_cvt_pk_bf16_f32 v49, v50, v51
	v_pk_fma_f32 v[54:55], v[54:55], v[8:9], v[86:87]
	v_pk_fma_f32 v[52:53], v[52:53], v[10:11], v[84:85]
	s_nop 0
	v_cvt_pk_bf16_f32 v50, v52, v53
	v_cvt_pk_bf16_f32 v51, v54, v55
	global_store_dwordx4 v[2:3], v[48:51], off offset:2048
	v_mov_b32_e32 v52, v105
	v_mov_b32_e32 v53, v111
	v_mov_b32_e32 v48, v93
	v_mov_b32_e32 v49, v95
	v_pk_mul_f32 v[48:49], v[26:27], v[48:49] op_sel_hi:[0,1]
	v_mov_b32_e32 v50, v99
	v_mov_b32_e32 v51, v103
	v_pk_mul_f32 v[50:51], v[26:27], v[50:51] op_sel_hi:[0,1]
	v_pk_fma_f32 v[48:49], v[48:49], v[14:15], v[80:81]
	v_mov_b32_e32 v54, v113
	v_mov_b32_e32 v55, v115
	v_pk_fma_f32 v[50:51], v[50:51], v[12:13], v[82:83]
	v_pk_mul_f32 v[52:53], v[26:27], v[52:53] op_sel_hi:[0,1]
	v_pk_mul_f32 v[54:55], v[26:27], v[54:55] op_sel_hi:[0,1]
	v_cvt_pk_bf16_f32 v48, v48, v49
	v_cvt_pk_bf16_f32 v49, v50, v51
	v_mov_b32_e32 v93, v94
	v_pk_fma_f32 v[54:55], v[54:55], v[8:9], v[86:87]
	v_pk_fma_f32 v[52:53], v[52:53], v[10:11], v[84:85]
	v_mov_b32_e32 v99, v102
	v_cvt_pk_bf16_f32 v50, v52, v53
	v_cvt_pk_bf16_f32 v51, v54, v55
	global_store_dwordx4 v[4:5], v[48:51], off offset:2048
	v_mov_b32_e32 v105, v110
	v_mov_b32_e32 v113, v114
	v_pk_mul_f32 v[48:49], v[24:25], v[92:93] op_sel_hi:[0,1]
	v_pk_mul_f32 v[50:51], v[24:25], v[98:99] op_sel_hi:[0,1]
	v_pk_fma_f32 v[14:15], v[48:49], v[14:15], v[80:81]
	v_pk_mul_f32 v[48:49], v[24:25], v[104:105] op_sel_hi:[0,1]
	v_pk_fma_f32 v[12:13], v[50:51], v[12:13], v[82:83]
	v_pk_mul_f32 v[50:51], v[24:25], v[112:113] op_sel_hi:[0,1]
	v_pk_fma_f32 v[10:11], v[48:49], v[10:11], v[84:85]
	v_pk_fma_f32 v[50:51], v[50:51], v[8:9], v[86:87]
	v_cvt_pk_bf16_f32 v8, v14, v15
	v_cvt_pk_bf16_f32 v9, v12, v13
	v_cvt_pk_bf16_f32 v10, v10, v11
	v_lshl_add_u64 v[12:13], v[136:137], 0, v[176:177]
	v_cvt_pk_bf16_f32 v11, v50, v51
	global_store_dwordx4 v[6:7], v[8:11], off offset:2048
	global_load_dwordx4 v[48:51], v176, s[2:3] offset:16
	s_nop 0
	global_load_dwordx4 v[8:11], v176, s[2:3]
	global_load_dwordx4 v[52:55], v[12:13], off offset:16
	s_nop 0
	global_load_dwordx4 v[12:15], v[12:13], off
	s_nop 0
	global_load_dwordx4 v[56:59], v[66:67], off offset:16
	global_load_dwordx4 v[72:75], v[66:67], off
	v_lshl_add_u64 v[224:225], v[116:117], 0, v[176:177]
	v_lshl_add_u64 v[226:227], v[118:119], 0, v[176:177]
	global_load_dwordx4 v[208:211], v[224:225], off offset:16
	global_load_dwordx4 v[212:215], v[224:225], off
	global_load_dwordx4 v[216:219], v[226:227], off offset:16
	global_load_dwordx4 v[220:223], v[226:227], off
	s_waitcnt vmcnt(0)
	v_pk_add_f32 v[14:15], v[14:15], v[74:75]
	v_pk_add_f32 v[12:13], v[12:13], v[72:73]
	v_pk_add_f32 v[14:15], v[14:15], 1.0 op_sel_hi:[1,0]
	v_pk_add_f32 v[66:67], v[12:13], 1.0 op_sel_hi:[1,0]
	v_pk_mul_f32 v[12:13], v[10:11], v[14:15]
	v_pk_mul_f32 v[14:15], v[8:9], v[66:67]
	v_pk_add_f32 v[8:9], v[54:55], v[58:59]
	v_pk_add_f32 v[10:11], v[52:53], v[56:57]
	v_pk_add_f32 v[8:9], v[8:9], 1.0 op_sel_hi:[1,0]
	v_pk_add_f32 v[10:11], v[10:11], 1.0 op_sel_hi:[1,0]
	v_pk_mul_f32 v[8:9], v[50:51], v[8:9]
	v_pk_mul_f32 v[10:11], v[48:49], v[10:11]
	v_pk_add_f32 v[56:57], v[208:209], v[216:217]
	v_mov_b32_e32 v48, v68
	v_mov_b32_e32 v49, v60
	v_mov_b32_e32 v60, v69
	v_pk_add_f32 v[54:55], v[214:215], v[222:223]
	v_pk_add_f32 v[52:53], v[212:213], v[220:221]
	v_pk_add_f32 v[58:59], v[210:211], v[218:219]
	v_pk_mul_f32 v[48:49], v[40:41], v[48:49] op_sel_hi:[0,1]
	v_pk_mul_f32 v[50:51], v[40:41], v[60:61] op_sel_hi:[0,1]
	v_mov_b32_e32 v60, v70
	v_mov_b32_e32 v61, v62
	v_mov_b32_e32 v62, v71
	v_pk_fma_f32 v[50:51], v[50:51], v[12:13], v[54:55]
	v_pk_fma_f32 v[48:49], v[48:49], v[14:15], v[52:53]
	v_pk_mul_f32 v[60:61], v[40:41], v[60:61] op_sel_hi:[0,1]
	v_pk_mul_f32 v[40:41], v[40:41], v[62:63] op_sel_hi:[0,1]
	v_pk_fma_f32 v[40:41], v[40:41], v[8:9], v[58:59]
	v_pk_fma_f32 v[60:61], v[60:61], v[10:11], v[56:57]
	v_cvt_pk_bf16_f32 v48, v48, v49
	v_cvt_pk_bf16_f32 v49, v50, v51
	s_nop 0
	v_cvt_pk_bf16_f32 v50, v60, v61
	v_cvt_pk_bf16_f32 v51, v40, v41
	global_store_dwordx4 v[0:1], v[48:51], off offset:3072
	v_mov_b32_e32 v0, v44
	v_mov_b32_e32 v1, v36
	v_pk_mul_f32 v[0:1], v[38:39], v[0:1] op_sel_hi:[0,1]
	v_mov_b32_e32 v41, v34
	v_mov_b32_e32 v34, v33
	v_mov_b32_e32 v36, v45
	v_pk_fma_f32 v[0:1], v[0:1], v[14:15], v[52:53]
	v_mov_b32_e32 v40, v32
	v_pk_mul_f32 v[32:33], v[38:39], v[34:35] op_sel_hi:[0,1]
	v_pk_mul_f32 v[36:37], v[38:39], v[36:37] op_sel_hi:[0,1]
	v_pk_mul_f32 v[40:41], v[38:39], v[40:41] op_sel_hi:[0,1]
	v_pk_fma_f32 v[38:39], v[32:33], v[8:9], v[58:59]
	v_cvt_pk_bf16_f32 v32, v0, v1
	v_mov_b32_e32 v0, v42
	v_mov_b32_e32 v1, v28
	v_pk_fma_f32 v[34:35], v[40:41], v[10:11], v[56:57]
	v_pk_mul_f32 v[0:1], v[26:27], v[0:1] op_sel_hi:[0,1]
	v_mov_b32_e32 v28, v43
	v_pk_fma_f32 v[36:37], v[36:37], v[12:13], v[54:55]
	v_pk_fma_f32 v[0:1], v[0:1], v[14:15], v[52:53]
	v_cvt_pk_bf16_f32 v33, v36, v37
	v_cvt_pk_bf16_f32 v34, v34, v35
	v_cvt_pk_bf16_f32 v35, v38, v39
	global_store_dwordx4 v[2:3], v[32:35], off offset:3072
	v_pk_mul_f32 v[2:3], v[26:27], v[28:29] op_sel_hi:[0,1]
	v_mov_b32_e32 v28, v46
	v_mov_b32_e32 v29, v30
	v_mov_b32_e32 v30, v47
	v_pk_fma_f32 v[2:3], v[2:3], v[12:13], v[54:55]
	v_pk_mul_f32 v[28:29], v[26:27], v[28:29] op_sel_hi:[0,1]
	v_pk_mul_f32 v[26:27], v[26:27], v[30:31] op_sel_hi:[0,1]
	v_cvt_pk_bf16_f32 v0, v0, v1
	v_cvt_pk_bf16_f32 v1, v2, v3
	v_pk_fma_f32 v[26:27], v[26:27], v[8:9], v[58:59]
	v_pk_fma_f32 v[28:29], v[28:29], v[10:11], v[56:57]
	s_nop 0
	v_cvt_pk_bf16_f32 v2, v28, v29
	v_cvt_pk_bf16_f32 v3, v26, v27
	global_store_dwordx4 v[4:5], v[0:3], off offset:3072
	v_mov_b32_e32 v4, v22
	v_mov_b32_e32 v5, v18
	v_mov_b32_e32 v0, v16
	v_mov_b32_e32 v1, v20
	v_mov_b32_e32 v20, v17
	v_pk_mul_f32 v[0:1], v[24:25], v[0:1] op_sel_hi:[0,1]
	v_pk_mul_f32 v[2:3], v[24:25], v[20:21] op_sel_hi:[0,1]
	v_mov_b32_e32 v18, v23
	v_pk_fma_f32 v[2:3], v[2:3], v[12:13], v[54:55]
	v_pk_fma_f32 v[0:1], v[0:1], v[14:15], v[52:53]
	v_pk_mul_f32 v[4:5], v[24:25], v[4:5] op_sel_hi:[0,1]
	v_pk_mul_f32 v[12:13], v[24:25], v[18:19] op_sel_hi:[0,1]
	v_pk_fma_f32 v[8:9], v[12:13], v[8:9], v[58:59]
	v_pk_fma_f32 v[4:5], v[4:5], v[10:11], v[56:57]
	v_cvt_pk_bf16_f32 v0, v0, v1
	v_cvt_pk_bf16_f32 v1, v2, v3
	s_nop 0
	v_cvt_pk_bf16_f32 v2, v4, v5
	v_cvt_pk_bf16_f32 v3, v8, v9
	global_store_dwordx4 v[6:7], v[0:3], off offset:3072
	s_cbranch_scc0 .LBB0_762
